# gain vectors preloaded outside the resid row loops (no per-step vmcnt0), non-leader workgroups poll the top-level barrier generation word, GEMM mainloop heads 64B-aligned+48
# baseline (speedup 1.0000x reference)
; #define PG8_STAGE(bufoff, gbase, voff) do { _Pragma("unroll") for (int _i = 0; _i < 2; ++_i) \
;         __builtin_amdgcn_global_load_lds((const unsigned*)((const char*)(gbase) + (voff)[_i]), (LAS unsigned*)(lds + (bufoff) + ldsw + _i * 8192), 16, 0, 0); } while (0)
; #define PG8_WAIT_V(n) asm volatile("s_waitcnt vmcnt(" #n ")" ::: "memory")
; #define PG8_BAR __builtin_amdgcn_s_barrier()
; template <class EpiT>
; __device__ __forceinline__ void gemm_phase(LAS unsigned char* lds, const Gemm g, const StaticOrder& S, const EpiT& E) {
;     ...
;     f32x4 acc[2][2][4][2];
; #pragma unroll
;     for (int a = 0; a < 2; ++a)
; #pragma unroll
;         for (int b = 0; b < 2; ++b)
; #pragma unroll
;             for (int m = 0; m < 4; ++m)
; #pragma unroll
;                 for (int n = 0; n < 2; ++n) acc[a][b][m][n] = (f32x4){0.f, 0.f, 0.f, 0.f};
;     bf16x8 At[4][2], B0[2][2], B1[2][2];
;     const char* cA = (const char*)g.A + (size_t)cur.pm * tstepA + (size_t)cur.pn * g.a_koff * 2; const char* cB = (const char*)g.Bt + (size_t)cur.pn * tstepB;
;     PG8_STAGE(PG8_SB(0, 0), cB, voffB); PG8_STAGE(PG8_SB(0, 1), cB + hstepB, voffB); PG8_STAGE(PG8_SA(0, 0), cA, voffA); PG8_STAGE(PG8_SA(0, 1), cA + hstepA, voffA);
;     if (wr == 1) PG8_BAR;
;     PG8_WAIT_V(2); PG8_BAR;
;     PG8_STAGE(PG8_SB(1, 0), cB + kstep, voffB); PG8_STAGE(PG8_SA(1, 0), cA + kstep, voffA); PG8_STAGE(PG8_SB(1, 1), cB + hstepB + kstep, voffB);
;     PG8_WAIT_V(6); PG8_BAR;
;     for (;;) {
;         const bool has_next = S.next(ui + 1, nxt);
;         const char* nA = has_next ? (const char*)g.A + (size_t)nxt.pm * tstepA + (size_t)nxt.pn * g.a_koff * 2 : cA; const char* nB = has_next ? (const char*)g.Bt + (size_t)nxt.pn * tstepB : cB;
;         for (int t = 0; t < nt; t += 2) {
.LBB0_99:
	s_add_u32 s16, s16, 0x84080
	s_addc_u32 s17, s17, 0
	s_add_u32 s51, s18, 0x100
	v_mov_b32_e32 v0, 0
	s_addc_u32 s52, s19, 0
	s_mov_b32 s53, -2
	v_mov_b32_e32 v1, v0
	v_mov_b32_e32 v2, v0
	v_mov_b32_e32 v3, v0
	v_mov_b32_e32 v4, v0
	v_mov_b32_e32 v5, v0
	v_mov_b32_e32 v6, v0
	v_mov_b32_e32 v7, v0
	v_mov_b32_e32 v16, v0
	v_mov_b32_e32 v17, v0
	v_mov_b32_e32 v18, v0
	v_mov_b32_e32 v19, v0
	v_mov_b32_e32 v20, v0
	v_mov_b32_e32 v21, v0
	v_mov_b32_e32 v22, v0
	v_mov_b32_e32 v23, v0
	v_mov_b32_e32 v32, v0
	v_mov_b32_e32 v33, v0
	v_mov_b32_e32 v34, v0
	v_mov_b32_e32 v35, v0
	v_mov_b32_e32 v36, v0
	v_mov_b32_e32 v37, v0
	v_mov_b32_e32 v38, v0
	v_mov_b32_e32 v39, v0
	v_mov_b32_e32 v48, v0
	v_mov_b32_e32 v49, v0
	v_mov_b32_e32 v50, v0
	v_mov_b32_e32 v51, v0
	v_mov_b32_e32 v52, v0
	v_mov_b32_e32 v53, v0
	v_mov_b32_e32 v54, v0
	v_mov_b32_e32 v55, v0
	v_mov_b32_e32 v8, v0
	v_mov_b32_e32 v9, v0
	v_mov_b32_e32 v10, v0
	v_mov_b32_e32 v11, v0
	v_mov_b32_e32 v12, v0
	v_mov_b32_e32 v13, v0
	v_mov_b32_e32 v14, v0
	v_mov_b32_e32 v15, v0
	v_mov_b32_e32 v24, v0
	v_mov_b32_e32 v25, v0
	v_mov_b32_e32 v26, v0
	v_mov_b32_e32 v27, v0
	v_mov_b32_e32 v28, v0
	v_mov_b32_e32 v29, v0
	v_mov_b32_e32 v30, v0
	v_mov_b32_e32 v31, v0
	v_mov_b32_e32 v40, v0
	v_mov_b32_e32 v41, v0
	v_mov_b32_e32 v42, v0
	v_mov_b32_e32 v43, v0
	v_mov_b32_e32 v44, v0
	v_mov_b32_e32 v45, v0
	v_mov_b32_e32 v46, v0
	v_mov_b32_e32 v47, v0
	v_mov_b32_e32 v56, v0
	v_mov_b32_e32 v57, v0
	v_mov_b32_e32 v58, v0
	v_mov_b32_e32 v59, v0
	v_mov_b32_e32 v60, v0
	v_mov_b32_e32 v61, v0
	v_mov_b32_e32 v62, v0
	v_mov_b32_e32 v63, v0
	v_mov_b32_e32 v64, v0
	v_mov_b32_e32 v65, v0
	v_mov_b32_e32 v66, v0
	v_mov_b32_e32 v67, v0
	v_mov_b32_e32 v68, v0
	v_mov_b32_e32 v69, v0
	v_mov_b32_e32 v70, v0
	v_mov_b32_e32 v71, v0
	v_mov_b32_e32 v80, v0
	v_mov_b32_e32 v81, v0
	v_mov_b32_e32 v82, v0
	v_mov_b32_e32 v83, v0
	v_mov_b32_e32 v84, v0
	v_mov_b32_e32 v85, v0
	v_mov_b32_e32 v86, v0
	v_mov_b32_e32 v87, v0
	v_mov_b32_e32 v96, v0
	v_mov_b32_e32 v97, v0
	v_mov_b32_e32 v98, v0
	v_mov_b32_e32 v99, v0
	v_mov_b32_e32 v100, v0
	v_mov_b32_e32 v101, v0
	v_mov_b32_e32 v102, v0
	v_mov_b32_e32 v103, v0
	v_mov_b32_e32 v112, v0
	v_mov_b32_e32 v113, v0
	v_mov_b32_e32 v114, v0
	v_mov_b32_e32 v115, v0
	v_mov_b32_e32 v116, v0
	v_mov_b32_e32 v117, v0
	v_mov_b32_e32 v118, v0
	v_mov_b32_e32 v119, v0
	v_mov_b32_e32 v72, v0
	v_mov_b32_e32 v73, v0
	v_mov_b32_e32 v74, v0
	v_mov_b32_e32 v75, v0
	v_mov_b32_e32 v76, v0
	v_mov_b32_e32 v77, v0
	v_mov_b32_e32 v78, v0
	v_mov_b32_e32 v79, v0
	v_mov_b32_e32 v88, v0
	v_mov_b32_e32 v89, v0
	v_mov_b32_e32 v90, v0
	v_mov_b32_e32 v91, v0
	v_mov_b32_e32 v92, v0
	v_mov_b32_e32 v93, v0
	v_mov_b32_e32 v94, v0
	v_mov_b32_e32 v95, v0
	v_mov_b32_e32 v104, v0
	v_mov_b32_e32 v105, v0
	v_mov_b32_e32 v106, v0
	v_mov_b32_e32 v107, v0
	v_mov_b32_e32 v108, v0
	v_mov_b32_e32 v109, v0
	v_mov_b32_e32 v110, v0
	v_mov_b32_e32 v111, v0
	v_mov_b32_e32 v120, v0
	v_mov_b32_e32 v121, v0
	v_mov_b32_e32 v122, v0
	v_mov_b32_e32 v123, v0
	v_mov_b32_e32 v124, v0
	v_mov_b32_e32 v125, v0
	v_mov_b32_e32 v126, v0
	v_mov_b32_e32 v127, v0
	.p2alignl 6, 3212836864
	s_nop 0
	s_nop 0
	s_nop 0
	s_nop 0
	s_nop 0
	s_nop 0
	s_nop 0
	s_nop 0
	s_nop 0
	s_nop 0
	s_nop 0
	s_nop 0

; #define LAS __attribute__((address_space(3)))
; #define ATT_LOAD(kp0_) do { _Pragma("unroll") for (int _i = 0; _i < 2; ++_i) { const int _grow = rowbase + ((kp0_) + srow + 32 * _i) * rowstride; \
;         kr[_i] = *(const u32x4*)(Kp + (size_t)_grow * ld + sch * 8); vr[_i] = *(const u32x4*)(Vp + (size_t)_grow * ld + sch * 8); } } while (0)
; template <int MODE> ...
;     ...
;     f32x4 o[2][8];
; #pragma unroll
;     for (int qt = 0; qt < 2; ++qt)
; #pragma unroll
;         for (int dt = 0; dt < 8; ++dt) o[qt][dt] = (f32x4){0.f, 0.f, 0.f, 0.f};
;     float mrun[2] = {-1e30f, -1e30f}, lrun[2] = {0.f, 0.f}, Rrun[2] = {1.f, 1.f};
;     const int srow = tid >> 4, sch = tid & 15;
;     ...
;     bf16x8 pf[2][2]; bool pend = false; int bcur = 0, bprev = 0;
;     if (!pre) ATT_LOAD(ATT_KP0(0));
; #pragma unroll
;     for (int i = 0; i < 2; ++i) { *(LAS u32x4*)(lds + KOFF + (srow + 32 * i) * ROWB + sch * 16) = kr[i]; *(LAS u32x4*)(lds + VOFF + (srow + 32 * i) * ROWB + sch * 16) = vr[i]; }
;     __syncthreads();
.LBB0_168:
	s_cmp_gt_i32 s10, 3
	s_cselect_b64 s[70:71], -1, 0
	s_cmp_lt_i32 s10, 4
	v_lshlrev_b32_e32 v18, 4, v16
	v_mul_lo_u32 v19, v169, s35
	s_cselect_b64 s[72:73], -1, 0
	v_add3_u32 v175, 0, v18, v19
	s_or_b32 s37, s67, 31
	s_add_i32 s36, s67, 0xffffff80
	s_add_i32 s89, s67, 0xffffff9f
	s_waitcnt vmcnt(0)
	ds_write_b128 v175, v[0:3]
	ds_write_b128 v175, v[4:7] offset:18432
	ds_write_b128 v175, v[8:11] offset:9216
	ds_write_b128 v175, v[12:15] offset:27648
	v_lshlrev_b32_e32 v167, 2, v165
	v_lshrrev_b32_e32 v0, 2, v16
	s_and_b64 s[0:1], s[0:1], exec
	v_or_b32_e32 v0, v167, v0
	s_cselect_b32 s38, s61, 0x140
	s_sub_i32 s0, s67, 17
	v_mul_u32_u24_e32 v170, 0x120, v0
	v_add_u32_e32 v0, s0, v16
	v_subrev_u32_e32 v0, s88, v0
	v_add_u32_e32 v178, s88, v167
	v_mov_b32_e32 v157, v147
	v_lshlrev_b32_e32 v1, 3, v17
	v_sub_u32_e32 v177, v0, v167
	v_sub_u32_e32 v0, v178, v16
	v_mov_b32_e32 v18, v147
	v_mov_b32_e32 v19, v147
	v_lshl_add_u64 v[158:159], s[2:3], 0, v[156:157]
	v_lshl_add_u64 v[160:161], s[4:5], 0, v[156:157]
	v_and_b32_e32 v157, 24, v1
	v_mul_u32_u24_e32 v173, 0x120, v16
	v_subrev_u32_e32 v0, s9, v0
	v_mov_b32_e32 v16, v147
	v_mov_b32_e32 v17, v147
	v_mov_b64_e32 v[22:23], v[18:19]
	v_mov_b64_e32 v[26:27], v[18:19]
	v_mov_b64_e32 v[30:31], v[18:19]
	v_mov_b64_e32 v[34:35], v[18:19]
	v_mov_b64_e32 v[38:39], v[18:19]
	v_mov_b64_e32 v[42:43], v[18:19]
	v_mov_b64_e32 v[46:47], v[18:19]
	v_mov_b64_e32 v[50:51], v[18:19]
	v_mov_b64_e32 v[54:55], v[18:19]
	v_mov_b64_e32 v[58:59], v[18:19]
	v_mov_b64_e32 v[62:63], v[18:19]
	v_mov_b64_e32 v[66:67], v[18:19]
	v_mov_b64_e32 v[70:71], v[18:19]
	v_mov_b64_e32 v[74:75], v[18:19]
	v_mov_b64_e32 v[78:79], v[18:19]
	v_ashrrev_i32_e32 v151, 31, v150
	v_mad_i64_i32 v[154:155], s[6:7], v150, s33, 0
	v_ashrrev_i32_e32 v149, 31, v148
	v_mad_i64_i32 v[152:153], s[6:7], v148, s33, 0
	v_add3_u32 v176, 0, v157, v170
	v_subrev_u32_e32 v179, s8, v0
	s_mov_b32 s45, 0
	s_mov_b64 s[74:75], 0
	v_mov_b32_e32 v163, 0
	v_mov_b32_e32 v181, 0xf149f2ca
	v_mov_b64_e32 v[20:21], v[16:17]
	v_mov_b64_e32 v[24:25], v[16:17]
	v_mov_b64_e32 v[28:29], v[16:17]
	v_mov_b64_e32 v[32:33], v[16:17]
	v_mov_b64_e32 v[36:37], v[16:17]
	v_mov_b64_e32 v[40:41], v[16:17]
	v_mov_b64_e32 v[44:45], v[16:17]
	v_mov_b64_e32 v[48:49], v[16:17]
	v_mov_b64_e32 v[52:53], v[16:17]
	v_mov_b64_e32 v[56:57], v[16:17]
	v_mov_b64_e32 v[60:61], v[16:17]
	v_mov_b64_e32 v[64:65], v[16:17]
	v_mov_b64_e32 v[68:69], v[16:17]
	v_mov_b64_e32 v[72:73], v[16:17]
	v_mov_b64_e32 v[76:77], v[16:17]
	v_mov_b32_e32 v182, 0xf149f2ca
	v_mov_b32_e32 v166, 0
	s_mov_b32 s0, 0
	s_mov_b32 s1, 0
	s_waitcnt lgkmcnt(0)
	s_barrier
	.p2alignl 6, 3212836864

; #define PG8_STAGE(bufoff, gbase, voff) do { _Pragma("unroll") for (int _i = 0; _i < 2; ++_i) \
;         __builtin_amdgcn_global_load_lds((const unsigned*)((const char*)(gbase) + (voff)[_i]), (LAS unsigned*)(lds + (bufoff) + ldsw + _i * 8192), 16, 0, 0); } while (0)
; #define PG8_WAIT_V(n) asm volatile("s_waitcnt vmcnt(" #n ")" ::: "memory")
; #define PG8_BAR __builtin_amdgcn_s_barrier()
; template <class EpiT>
; __device__ __forceinline__ void gemm_phase(LAS unsigned char* lds, const Gemm g, const StaticOrder& S, const EpiT& E) {
;     ...
;     f32x4 acc[2][2][4][2];
; #pragma unroll
;     for (int a = 0; a < 2; ++a)
; #pragma unroll
;         for (int b = 0; b < 2; ++b)
; #pragma unroll
;             for (int m = 0; m < 4; ++m)
; #pragma unroll
;                 for (int n = 0; n < 2; ++n) acc[a][b][m][n] = (f32x4){0.f, 0.f, 0.f, 0.f};
;     bf16x8 At[4][2], B0[2][2], B1[2][2];
;     const char* cA = (const char*)g.A + (size_t)cur.pm * tstepA + (size_t)cur.pn * g.a_koff * 2; const char* cB = (const char*)g.Bt + (size_t)cur.pn * tstepB;
;     PG8_STAGE(PG8_SB(0, 0), cB, voffB); PG8_STAGE(PG8_SB(0, 1), cB + hstepB, voffB); PG8_STAGE(PG8_SA(0, 0), cA, voffA); PG8_STAGE(PG8_SA(0, 1), cA + hstepA, voffA);
;     if (wr == 1) PG8_BAR;
;     PG8_WAIT_V(2); PG8_BAR;
;     PG8_STAGE(PG8_SB(1, 0), cB + kstep, voffB); PG8_STAGE(PG8_SA(1, 0), cA + kstep, voffA); PG8_STAGE(PG8_SB(1, 1), cB + hstepB + kstep, voffB);
;     PG8_WAIT_V(6); PG8_BAR;
;     for (;;) {
;         const bool has_next = S.next(ui + 1, nxt);
;         const char* nA = has_next ? (const char*)g.A + (size_t)nxt.pm * tstepA + (size_t)nxt.pn * g.a_koff * 2 : cA; const char* nB = has_next ? (const char*)g.Bt + (size_t)nxt.pn * tstepB : cB;
;         for (int t = 0; t < nt; t += 2) {
.LBB0_295:
	s_lshl_b64 s[4:5], s[16:17], 17
	s_add_u32 s22, s33, s4
	s_addc_u32 s23, s35, s5
	s_and_b64 s[4:5], s[2:3], exec
	v_mov_b32_e32 v0, 0
	s_cselect_b32 s17, s23, s47
	s_cselect_b32 s19, s22, s46
	s_mov_b32 s54, 0
	s_mov_b64 s[4:5], -1
	s_mov_b64 s[68:69], 0
	v_mov_b32_e32 v1, v0
	v_mov_b32_e32 v2, v0
	v_mov_b32_e32 v3, v0
	v_mov_b32_e32 v4, v0
	v_mov_b32_e32 v5, v0
	v_mov_b32_e32 v6, v0
	v_mov_b32_e32 v7, v0
	v_mov_b32_e32 v16, v0
	v_mov_b32_e32 v17, v0
	v_mov_b32_e32 v18, v0
	v_mov_b32_e32 v19, v0
	v_mov_b32_e32 v20, v0
	v_mov_b32_e32 v21, v0
	v_mov_b32_e32 v22, v0
	v_mov_b32_e32 v23, v0
	v_mov_b32_e32 v32, v0
	v_mov_b32_e32 v33, v0
	v_mov_b32_e32 v34, v0
	v_mov_b32_e32 v35, v0
	v_mov_b32_e32 v36, v0
	v_mov_b32_e32 v37, v0
	v_mov_b32_e32 v38, v0
	v_mov_b32_e32 v39, v0
	v_mov_b32_e32 v48, v0
	v_mov_b32_e32 v49, v0
	v_mov_b32_e32 v50, v0
	v_mov_b32_e32 v51, v0
	v_mov_b32_e32 v52, v0
	v_mov_b32_e32 v53, v0
	v_mov_b32_e32 v54, v0
	v_mov_b32_e32 v55, v0
	v_mov_b32_e32 v8, v0
	v_mov_b32_e32 v9, v0
	v_mov_b32_e32 v10, v0
	v_mov_b32_e32 v11, v0
	v_mov_b32_e32 v12, v0
	v_mov_b32_e32 v13, v0
	v_mov_b32_e32 v14, v0
	v_mov_b32_e32 v15, v0
	v_mov_b32_e32 v24, v0
	v_mov_b32_e32 v25, v0
	v_mov_b32_e32 v26, v0
	v_mov_b32_e32 v27, v0
	v_mov_b32_e32 v28, v0
	v_mov_b32_e32 v29, v0
	v_mov_b32_e32 v30, v0
	v_mov_b32_e32 v31, v0
	v_mov_b32_e32 v40, v0
	v_mov_b32_e32 v41, v0
	v_mov_b32_e32 v42, v0
	v_mov_b32_e32 v43, v0
	v_mov_b32_e32 v44, v0
	v_mov_b32_e32 v45, v0
	v_mov_b32_e32 v46, v0
	v_mov_b32_e32 v47, v0
	v_mov_b32_e32 v56, v0
	v_mov_b32_e32 v57, v0
	v_mov_b32_e32 v58, v0
	v_mov_b32_e32 v59, v0
	v_mov_b32_e32 v60, v0
	v_mov_b32_e32 v61, v0
	v_mov_b32_e32 v62, v0
	v_mov_b32_e32 v63, v0
	v_mov_b32_e32 v64, v0
	v_mov_b32_e32 v65, v0
	v_mov_b32_e32 v66, v0
	v_mov_b32_e32 v67, v0
	v_mov_b32_e32 v68, v0
	v_mov_b32_e32 v69, v0
	v_mov_b32_e32 v70, v0
	v_mov_b32_e32 v71, v0
	v_mov_b32_e32 v80, v0
	v_mov_b32_e32 v81, v0
	v_mov_b32_e32 v82, v0
	v_mov_b32_e32 v83, v0
	v_mov_b32_e32 v84, v0
	v_mov_b32_e32 v85, v0
	v_mov_b32_e32 v86, v0
	v_mov_b32_e32 v87, v0
	v_mov_b32_e32 v96, v0
	v_mov_b32_e32 v97, v0
	v_mov_b32_e32 v98, v0
	v_mov_b32_e32 v99, v0
	v_mov_b32_e32 v100, v0
	v_mov_b32_e32 v101, v0
	v_mov_b32_e32 v102, v0
	v_mov_b32_e32 v103, v0
	v_mov_b32_e32 v112, v0
	v_mov_b32_e32 v113, v0
	v_mov_b32_e32 v114, v0
	v_mov_b32_e32 v115, v0
	v_mov_b32_e32 v116, v0
	v_mov_b32_e32 v117, v0
	v_mov_b32_e32 v118, v0
	v_mov_b32_e32 v119, v0
	v_mov_b32_e32 v72, v0
	v_mov_b32_e32 v73, v0
	v_mov_b32_e32 v74, v0
	v_mov_b32_e32 v75, v0
	v_mov_b32_e32 v76, v0
	v_mov_b32_e32 v77, v0
	v_mov_b32_e32 v78, v0
	v_mov_b32_e32 v79, v0
	v_mov_b32_e32 v88, v0
	v_mov_b32_e32 v89, v0
	v_mov_b32_e32 v90, v0
	v_mov_b32_e32 v91, v0
	v_mov_b32_e32 v92, v0
	v_mov_b32_e32 v93, v0
	v_mov_b32_e32 v94, v0
	v_mov_b32_e32 v95, v0
	v_mov_b32_e32 v104, v0
	v_mov_b32_e32 v105, v0
	v_mov_b32_e32 v106, v0
	v_mov_b32_e32 v107, v0
	v_mov_b32_e32 v108, v0
	v_mov_b32_e32 v109, v0
	v_mov_b32_e32 v110, v0
	v_mov_b32_e32 v111, v0
	v_mov_b32_e32 v120, v0
	v_mov_b32_e32 v121, v0
	v_mov_b32_e32 v122, v0
	v_mov_b32_e32 v123, v0
	v_mov_b32_e32 v124, v0
	v_mov_b32_e32 v125, v0
	v_mov_b32_e32 v126, v0
	v_mov_b32_e32 v127, v0
	.p2alignl 6, 3212836864
	s_nop 0
	s_nop 0
	s_nop 0
	s_nop 0
	s_nop 0
	s_nop 0
	s_nop 0
	s_nop 0
	s_nop 0
	s_nop 0
	s_nop 0
	s_nop 0

; #define PG8_STAGE(bufoff, gbase, voff) do { _Pragma("unroll") for (int _i = 0; _i < 2; ++_i) \
;         __builtin_amdgcn_global_load_lds((const unsigned*)((const char*)(gbase) + (voff)[_i]), (LAS unsigned*)(lds + (bufoff) + ldsw + _i * 8192), 16, 0, 0); } while (0)
; #define PG8_WAIT_V(n) asm volatile("s_waitcnt vmcnt(" #n ")" ::: "memory")
; #define PG8_BAR __builtin_amdgcn_s_barrier()
; template <class EpiT>
; __device__ __forceinline__ void gemm_phase(LAS unsigned char* lds, const Gemm g, const StaticOrder& S, const EpiT& E) {
;     ...
;     f32x4 acc[2][2][4][2];
; #pragma unroll
;     for (int a = 0; a < 2; ++a)
; #pragma unroll
;         for (int b = 0; b < 2; ++b)
; #pragma unroll
;             for (int m = 0; m < 4; ++m)
; #pragma unroll
;                 for (int n = 0; n < 2; ++n) acc[a][b][m][n] = (f32x4){0.f, 0.f, 0.f, 0.f};
;     bf16x8 At[4][2], B0[2][2], B1[2][2];
;     const char* cA = (const char*)g.A + (size_t)cur.pm * tstepA + (size_t)cur.pn * g.a_koff * 2; const char* cB = (const char*)g.Bt + (size_t)cur.pn * tstepB;
;     PG8_STAGE(PG8_SB(0, 0), cB, voffB); PG8_STAGE(PG8_SB(0, 1), cB + hstepB, voffB); PG8_STAGE(PG8_SA(0, 0), cA, voffA); PG8_STAGE(PG8_SA(0, 1), cA + hstepA, voffA);
;     if (wr == 1) PG8_BAR;
;     PG8_WAIT_V(2); PG8_BAR;
;     PG8_STAGE(PG8_SB(1, 0), cB + kstep, voffB); PG8_STAGE(PG8_SA(1, 0), cA + kstep, voffA); PG8_STAGE(PG8_SB(1, 1), cB + hstepB + kstep, voffB);
;     PG8_WAIT_V(6); PG8_BAR;
;     for (;;) {
;         const bool has_next = S.next(ui + 1, nxt);
;         const char* nA = has_next ? (const char*)g.A + (size_t)nxt.pm * tstepA + (size_t)nxt.pn * g.a_koff * 2 : cA; const char* nB = has_next ? (const char*)g.Bt + (size_t)nxt.pn * tstepB : cB;
;         for (int t = 0; t < nt; t += 2) {
.LBB0_391:
	s_add_u32 s18, s18, 0x84080
	s_addc_u32 s19, s19, 0
	s_add_u32 s51, s20, 0x100
	v_mov_b32_e32 v0, 0
	s_addc_u32 s52, s21, 0
	s_mov_b32 s53, -2
	v_mov_b32_e32 v1, v0
	v_mov_b32_e32 v2, v0
	v_mov_b32_e32 v3, v0
	v_mov_b32_e32 v4, v0
	v_mov_b32_e32 v5, v0
	v_mov_b32_e32 v6, v0
	v_mov_b32_e32 v7, v0
	v_mov_b32_e32 v16, v0
	v_mov_b32_e32 v17, v0
	v_mov_b32_e32 v18, v0
	v_mov_b32_e32 v19, v0
	v_mov_b32_e32 v20, v0
	v_mov_b32_e32 v21, v0
	v_mov_b32_e32 v22, v0
	v_mov_b32_e32 v23, v0
	v_mov_b32_e32 v32, v0
	v_mov_b32_e32 v33, v0
	v_mov_b32_e32 v34, v0
	v_mov_b32_e32 v35, v0
	v_mov_b32_e32 v36, v0
	v_mov_b32_e32 v37, v0
	v_mov_b32_e32 v38, v0
	v_mov_b32_e32 v39, v0
	v_mov_b32_e32 v48, v0
	v_mov_b32_e32 v49, v0
	v_mov_b32_e32 v50, v0
	v_mov_b32_e32 v51, v0
	v_mov_b32_e32 v52, v0
	v_mov_b32_e32 v53, v0
	v_mov_b32_e32 v54, v0
	v_mov_b32_e32 v55, v0
	v_mov_b32_e32 v8, v0
	v_mov_b32_e32 v9, v0
	v_mov_b32_e32 v10, v0
	v_mov_b32_e32 v11, v0
	v_mov_b32_e32 v12, v0
	v_mov_b32_e32 v13, v0
	v_mov_b32_e32 v14, v0
	v_mov_b32_e32 v15, v0
	v_mov_b32_e32 v24, v0
	v_mov_b32_e32 v25, v0
	v_mov_b32_e32 v26, v0
	v_mov_b32_e32 v27, v0
	v_mov_b32_e32 v28, v0
	v_mov_b32_e32 v29, v0
	v_mov_b32_e32 v30, v0
	v_mov_b32_e32 v31, v0
	v_mov_b32_e32 v40, v0
	v_mov_b32_e32 v41, v0
	v_mov_b32_e32 v42, v0
	v_mov_b32_e32 v43, v0
	v_mov_b32_e32 v44, v0
	v_mov_b32_e32 v45, v0
	v_mov_b32_e32 v46, v0
	v_mov_b32_e32 v47, v0
	v_mov_b32_e32 v56, v0
	v_mov_b32_e32 v57, v0
	v_mov_b32_e32 v58, v0
	v_mov_b32_e32 v59, v0
	v_mov_b32_e32 v60, v0
	v_mov_b32_e32 v61, v0
	v_mov_b32_e32 v62, v0
	v_mov_b32_e32 v63, v0
	v_mov_b32_e32 v64, v0
	v_mov_b32_e32 v65, v0
	v_mov_b32_e32 v66, v0
	v_mov_b32_e32 v67, v0
	v_mov_b32_e32 v68, v0
	v_mov_b32_e32 v69, v0
	v_mov_b32_e32 v70, v0
	v_mov_b32_e32 v71, v0
	v_mov_b32_e32 v80, v0
	v_mov_b32_e32 v81, v0
	v_mov_b32_e32 v82, v0
	v_mov_b32_e32 v83, v0
	v_mov_b32_e32 v84, v0
	v_mov_b32_e32 v85, v0
	v_mov_b32_e32 v86, v0
	v_mov_b32_e32 v87, v0
	v_mov_b32_e32 v96, v0
	v_mov_b32_e32 v97, v0
	v_mov_b32_e32 v98, v0
	v_mov_b32_e32 v99, v0
	v_mov_b32_e32 v100, v0
	v_mov_b32_e32 v101, v0
	v_mov_b32_e32 v102, v0
	v_mov_b32_e32 v103, v0
	v_mov_b32_e32 v112, v0
	v_mov_b32_e32 v113, v0
	v_mov_b32_e32 v114, v0
	v_mov_b32_e32 v115, v0
	v_mov_b32_e32 v116, v0
	v_mov_b32_e32 v117, v0
	v_mov_b32_e32 v118, v0
	v_mov_b32_e32 v119, v0
	v_mov_b32_e32 v72, v0
	v_mov_b32_e32 v73, v0
	v_mov_b32_e32 v74, v0
	v_mov_b32_e32 v75, v0
	v_mov_b32_e32 v76, v0
	v_mov_b32_e32 v77, v0
	v_mov_b32_e32 v78, v0
	v_mov_b32_e32 v79, v0
	v_mov_b32_e32 v88, v0
	v_mov_b32_e32 v89, v0
	v_mov_b32_e32 v90, v0
	v_mov_b32_e32 v91, v0
	v_mov_b32_e32 v92, v0
	v_mov_b32_e32 v93, v0
	v_mov_b32_e32 v94, v0
	v_mov_b32_e32 v95, v0
	v_mov_b32_e32 v104, v0
	v_mov_b32_e32 v105, v0
	v_mov_b32_e32 v106, v0
	v_mov_b32_e32 v107, v0
	v_mov_b32_e32 v108, v0
	v_mov_b32_e32 v109, v0
	v_mov_b32_e32 v110, v0
	v_mov_b32_e32 v111, v0
	v_mov_b32_e32 v120, v0
	v_mov_b32_e32 v121, v0
	v_mov_b32_e32 v122, v0
	v_mov_b32_e32 v123, v0
	v_mov_b32_e32 v124, v0
	v_mov_b32_e32 v125, v0
	v_mov_b32_e32 v126, v0
	v_mov_b32_e32 v127, v0
	.p2alignl 6, 3212836864
	s_nop 0
	s_nop 0
	s_nop 0
	s_nop 0
	s_nop 0
	s_nop 0
	s_nop 0
	s_nop 0
	s_nop 0
	s_nop 0
	s_nop 0
	s_nop 0

; #define PG8_STAGE(bufoff, gbase, voff) do { _Pragma("unroll") for (int _i = 0; _i < 2; ++_i) \
;         __builtin_amdgcn_global_load_lds((const unsigned*)((const char*)(gbase) + (voff)[_i]), (LAS unsigned*)(lds + (bufoff) + ldsw + _i * 8192), 16, 0, 0); } while (0)
; #define PG8_WAIT_V(n) asm volatile("s_waitcnt vmcnt(" #n ")" ::: "memory")
; #define PG8_BAR __builtin_amdgcn_s_barrier()
; template <class EpiT>
; __device__ __forceinline__ void gemm_phase(LAS unsigned char* lds, const Gemm g, const StaticOrder& S, const EpiT& E) {
;     ...
;     f32x4 acc[2][2][4][2];
; #pragma unroll
;     for (int a = 0; a < 2; ++a)
; #pragma unroll
;         for (int b = 0; b < 2; ++b)
; #pragma unroll
;             for (int m = 0; m < 4; ++m)
; #pragma unroll
;                 for (int n = 0; n < 2; ++n) acc[a][b][m][n] = (f32x4){0.f, 0.f, 0.f, 0.f};
;     bf16x8 At[4][2], B0[2][2], B1[2][2];
;     const char* cA = (const char*)g.A + (size_t)cur.pm * tstepA + (size_t)cur.pn * g.a_koff * 2; const char* cB = (const char*)g.Bt + (size_t)cur.pn * tstepB;
;     PG8_STAGE(PG8_SB(0, 0), cB, voffB); PG8_STAGE(PG8_SB(0, 1), cB + hstepB, voffB); PG8_STAGE(PG8_SA(0, 0), cA, voffA); PG8_STAGE(PG8_SA(0, 1), cA + hstepA, voffA);
;     if (wr == 1) PG8_BAR;
;     PG8_WAIT_V(2); PG8_BAR;
;     PG8_STAGE(PG8_SB(1, 0), cB + kstep, voffB); PG8_STAGE(PG8_SA(1, 0), cA + kstep, voffA); PG8_STAGE(PG8_SB(1, 1), cB + hstepB + kstep, voffB);
;     PG8_WAIT_V(6); PG8_BAR;
;     for (;;) {
;         const bool has_next = S.next(ui + 1, nxt);
;         const char* nA = has_next ? (const char*)g.A + (size_t)nxt.pm * tstepA + (size_t)nxt.pn * g.a_koff * 2 : cA; const char* nB = has_next ? (const char*)g.Bt + (size_t)nxt.pn * tstepB : cB;
;         for (int t = 0; t < nt; t += 2) {
.LBB0_594:
	s_add_u32 s18, s18, 0x164080
	s_addc_u32 s19, s19, 0
	s_add_u32 s53, s20, 0x100
	v_mov_b32_e32 v0, 0
	s_addc_u32 s54, s21, 0
	s_mov_b32 s55, -2
	v_mov_b32_e32 v1, v0
	v_mov_b32_e32 v2, v0
	v_mov_b32_e32 v3, v0
	v_mov_b32_e32 v4, v0
	v_mov_b32_e32 v5, v0
	v_mov_b32_e32 v6, v0
	v_mov_b32_e32 v7, v0
	v_mov_b32_e32 v16, v0
	v_mov_b32_e32 v17, v0
	v_mov_b32_e32 v18, v0
	v_mov_b32_e32 v19, v0
	v_mov_b32_e32 v20, v0
	v_mov_b32_e32 v21, v0
	v_mov_b32_e32 v22, v0
	v_mov_b32_e32 v23, v0
	v_mov_b32_e32 v32, v0
	v_mov_b32_e32 v33, v0
	v_mov_b32_e32 v34, v0
	v_mov_b32_e32 v35, v0
	v_mov_b32_e32 v36, v0
	v_mov_b32_e32 v37, v0
	v_mov_b32_e32 v38, v0
	v_mov_b32_e32 v39, v0
	v_mov_b32_e32 v48, v0
	v_mov_b32_e32 v49, v0
	v_mov_b32_e32 v50, v0
	v_mov_b32_e32 v51, v0
	v_mov_b32_e32 v52, v0
	v_mov_b32_e32 v53, v0
	v_mov_b32_e32 v54, v0
	v_mov_b32_e32 v55, v0
	v_mov_b32_e32 v8, v0
	v_mov_b32_e32 v9, v0
	v_mov_b32_e32 v10, v0
	v_mov_b32_e32 v11, v0
	v_mov_b32_e32 v12, v0
	v_mov_b32_e32 v13, v0
	v_mov_b32_e32 v14, v0
	v_mov_b32_e32 v15, v0
	v_mov_b32_e32 v24, v0
	v_mov_b32_e32 v25, v0
	v_mov_b32_e32 v26, v0
	v_mov_b32_e32 v27, v0
	v_mov_b32_e32 v28, v0
	v_mov_b32_e32 v29, v0
	v_mov_b32_e32 v30, v0
	v_mov_b32_e32 v31, v0
	v_mov_b32_e32 v40, v0
	v_mov_b32_e32 v41, v0
	v_mov_b32_e32 v42, v0
	v_mov_b32_e32 v43, v0
	v_mov_b32_e32 v44, v0
	v_mov_b32_e32 v45, v0
	v_mov_b32_e32 v46, v0
	v_mov_b32_e32 v47, v0
	v_mov_b32_e32 v56, v0
	v_mov_b32_e32 v57, v0
	v_mov_b32_e32 v58, v0
	v_mov_b32_e32 v59, v0
	v_mov_b32_e32 v60, v0
	v_mov_b32_e32 v61, v0
	v_mov_b32_e32 v62, v0
	v_mov_b32_e32 v63, v0
	v_mov_b32_e32 v64, v0
	v_mov_b32_e32 v65, v0
	v_mov_b32_e32 v66, v0
	v_mov_b32_e32 v67, v0
	v_mov_b32_e32 v68, v0
	v_mov_b32_e32 v69, v0
	v_mov_b32_e32 v70, v0
	v_mov_b32_e32 v71, v0
	v_mov_b32_e32 v80, v0
	v_mov_b32_e32 v81, v0
	v_mov_b32_e32 v82, v0
	v_mov_b32_e32 v83, v0
	v_mov_b32_e32 v84, v0
	v_mov_b32_e32 v85, v0
	v_mov_b32_e32 v86, v0
	v_mov_b32_e32 v87, v0
	v_mov_b32_e32 v96, v0
	v_mov_b32_e32 v97, v0
	v_mov_b32_e32 v98, v0
	v_mov_b32_e32 v99, v0
	v_mov_b32_e32 v100, v0
	v_mov_b32_e32 v101, v0
	v_mov_b32_e32 v102, v0
	v_mov_b32_e32 v103, v0
	v_mov_b32_e32 v112, v0
	v_mov_b32_e32 v113, v0
	v_mov_b32_e32 v114, v0
	v_mov_b32_e32 v115, v0
	v_mov_b32_e32 v116, v0
	v_mov_b32_e32 v117, v0
	v_mov_b32_e32 v118, v0
	v_mov_b32_e32 v119, v0
	v_mov_b32_e32 v72, v0
	v_mov_b32_e32 v73, v0
	v_mov_b32_e32 v74, v0
	v_mov_b32_e32 v75, v0
	v_mov_b32_e32 v76, v0
	v_mov_b32_e32 v77, v0
	v_mov_b32_e32 v78, v0
	v_mov_b32_e32 v79, v0
	v_mov_b32_e32 v88, v0
	v_mov_b32_e32 v89, v0
	v_mov_b32_e32 v90, v0
	v_mov_b32_e32 v91, v0
	v_mov_b32_e32 v92, v0
	v_mov_b32_e32 v93, v0
	v_mov_b32_e32 v94, v0
	v_mov_b32_e32 v95, v0
	v_mov_b32_e32 v104, v0
	v_mov_b32_e32 v105, v0
	v_mov_b32_e32 v106, v0
	v_mov_b32_e32 v107, v0
	v_mov_b32_e32 v108, v0
	v_mov_b32_e32 v109, v0
	v_mov_b32_e32 v110, v0
	v_mov_b32_e32 v111, v0
	v_mov_b32_e32 v120, v0
	v_mov_b32_e32 v121, v0
	v_mov_b32_e32 v122, v0
	v_mov_b32_e32 v123, v0
	v_mov_b32_e32 v124, v0
	v_mov_b32_e32 v125, v0
	v_mov_b32_e32 v126, v0
	v_mov_b32_e32 v127, v0
	.p2alignl 6, 3212836864
	s_nop 0
	s_nop 0
	s_nop 0
	s_nop 0
	s_nop 0
	s_nop 0
	s_nop 0
	s_nop 0
	s_nop 0
	s_nop 0
	s_nop 0
	s_nop 0

; #define PG8_STAGE(bufoff, gbase, voff) do { _Pragma("unroll") for (int _i = 0; _i < 2; ++_i) \
;         __builtin_amdgcn_global_load_lds((const unsigned*)((const char*)(gbase) + (voff)[_i]), (LAS unsigned*)(lds + (bufoff) + ldsw + _i * 8192), 16, 0, 0); } while (0)
; #define PG8_WAIT_V(n) asm volatile("s_waitcnt vmcnt(" #n ")" ::: "memory")
; #define PG8_BAR __builtin_amdgcn_s_barrier()
; template <class EpiT>
; __device__ __forceinline__ void gemm_phase(LAS unsigned char* lds, const Gemm g, const StaticOrder& S, const EpiT& E) {
;     ...
;     f32x4 acc[2][2][4][2];
; #pragma unroll
;     for (int a = 0; a < 2; ++a)
; #pragma unroll
;         for (int b = 0; b < 2; ++b)
; #pragma unroll
;             for (int m = 0; m < 4; ++m)
; #pragma unroll
;                 for (int n = 0; n < 2; ++n) acc[a][b][m][n] = (f32x4){0.f, 0.f, 0.f, 0.f};
;     bf16x8 At[4][2], B0[2][2], B1[2][2];
;     const char* cA = (const char*)g.A + (size_t)cur.pm * tstepA + (size_t)cur.pn * g.a_koff * 2; const char* cB = (const char*)g.Bt + (size_t)cur.pn * tstepB;
;     PG8_STAGE(PG8_SB(0, 0), cB, voffB); PG8_STAGE(PG8_SB(0, 1), cB + hstepB, voffB); PG8_STAGE(PG8_SA(0, 0), cA, voffA); PG8_STAGE(PG8_SA(0, 1), cA + hstepA, voffA);
;     if (wr == 1) PG8_BAR;
;     PG8_WAIT_V(2); PG8_BAR;
;     PG8_STAGE(PG8_SB(1, 0), cB + kstep, voffB); PG8_STAGE(PG8_SA(1, 0), cA + kstep, voffA); PG8_STAGE(PG8_SB(1, 1), cB + hstepB + kstep, voffB);
;     PG8_WAIT_V(6); PG8_BAR;
;     for (;;) {
;         const bool has_next = S.next(ui + 1, nxt);
;         const char* nA = has_next ? (const char*)g.A + (size_t)nxt.pm * tstepA + (size_t)nxt.pn * g.a_koff * 2 : cA; const char* nB = has_next ? (const char*)g.Bt + (size_t)nxt.pn * tstepB : cB;
;         for (int t = 0; t < nt; t += 2) {
.LBB0_760:
	s_add_u32 s20, s20, 0x84080
	s_addc_u32 s21, s21, 0
	s_add_u32 s8, s22, 0x100
	v_mov_b32_e32 v0, 0
	s_addc_u32 s39, s23, 0
	s_mov_b32 s56, -2
	s_waitcnt lgkmcnt(0)
	v_mov_b32_e32 v1, v0
	v_mov_b32_e32 v2, v0
	v_mov_b32_e32 v3, v0
	v_mov_b32_e32 v4, v0
	v_mov_b32_e32 v5, v0
	v_mov_b32_e32 v6, v0
	v_mov_b32_e32 v7, v0
	v_mov_b32_e32 v16, v0
	v_mov_b32_e32 v17, v0
	v_mov_b32_e32 v18, v0
	v_mov_b32_e32 v19, v0
	v_mov_b32_e32 v20, v0
	v_mov_b32_e32 v21, v0
	v_mov_b32_e32 v22, v0
	v_mov_b32_e32 v23, v0
	v_mov_b32_e32 v32, v0
	v_mov_b32_e32 v33, v0
	v_mov_b32_e32 v34, v0
	v_mov_b32_e32 v35, v0
	v_mov_b32_e32 v36, v0
	v_mov_b32_e32 v37, v0
	v_mov_b32_e32 v38, v0
	v_mov_b32_e32 v39, v0
	v_mov_b32_e32 v48, v0
	v_mov_b32_e32 v49, v0
	v_mov_b32_e32 v50, v0
	v_mov_b32_e32 v51, v0
	v_mov_b32_e32 v52, v0
	v_mov_b32_e32 v53, v0
	v_mov_b32_e32 v54, v0
	v_mov_b32_e32 v55, v0
	v_mov_b32_e32 v8, v0
	v_mov_b32_e32 v9, v0
	v_mov_b32_e32 v10, v0
	v_mov_b32_e32 v11, v0
	v_mov_b32_e32 v12, v0
	v_mov_b32_e32 v13, v0
	v_mov_b32_e32 v14, v0
	v_mov_b32_e32 v15, v0
	v_mov_b32_e32 v24, v0
	v_mov_b32_e32 v25, v0
	v_mov_b32_e32 v26, v0
	v_mov_b32_e32 v27, v0
	v_mov_b32_e32 v28, v0
	v_mov_b32_e32 v29, v0
	v_mov_b32_e32 v30, v0
	v_mov_b32_e32 v31, v0
	v_mov_b32_e32 v40, v0
	v_mov_b32_e32 v41, v0
	v_mov_b32_e32 v42, v0
	v_mov_b32_e32 v43, v0
	v_mov_b32_e32 v44, v0
	v_mov_b32_e32 v45, v0
	v_mov_b32_e32 v46, v0
	v_mov_b32_e32 v47, v0
	v_mov_b32_e32 v56, v0
	v_mov_b32_e32 v57, v0
	v_mov_b32_e32 v58, v0
	v_mov_b32_e32 v59, v0
	v_mov_b32_e32 v60, v0
	v_mov_b32_e32 v61, v0
	v_mov_b32_e32 v62, v0
	v_mov_b32_e32 v63, v0
	v_mov_b32_e32 v64, v0
	v_mov_b32_e32 v65, v0
	v_mov_b32_e32 v66, v0
	v_mov_b32_e32 v67, v0
	v_mov_b32_e32 v68, v0
	v_mov_b32_e32 v69, v0
	v_mov_b32_e32 v70, v0
	v_mov_b32_e32 v71, v0
	v_mov_b32_e32 v80, v0
	v_mov_b32_e32 v81, v0
	v_mov_b32_e32 v82, v0
	v_mov_b32_e32 v83, v0
	v_mov_b32_e32 v84, v0
	v_mov_b32_e32 v85, v0
	v_mov_b32_e32 v86, v0
	v_mov_b32_e32 v87, v0
	v_mov_b32_e32 v96, v0
	v_mov_b32_e32 v97, v0
	v_mov_b32_e32 v98, v0
	v_mov_b32_e32 v99, v0
	v_mov_b32_e32 v100, v0
	v_mov_b32_e32 v101, v0
	v_mov_b32_e32 v102, v0
	v_mov_b32_e32 v103, v0
	v_mov_b32_e32 v112, v0
	v_mov_b32_e32 v113, v0
	v_mov_b32_e32 v114, v0
	v_mov_b32_e32 v115, v0
	v_mov_b32_e32 v116, v0
	v_mov_b32_e32 v117, v0
	v_mov_b32_e32 v118, v0
	v_mov_b32_e32 v119, v0
	v_mov_b32_e32 v72, v0
	v_mov_b32_e32 v73, v0
	v_mov_b32_e32 v74, v0
	v_mov_b32_e32 v75, v0
	v_mov_b32_e32 v76, v0
	v_mov_b32_e32 v77, v0
	v_mov_b32_e32 v78, v0
	v_mov_b32_e32 v79, v0
	v_mov_b32_e32 v88, v0
	v_mov_b32_e32 v89, v0
	v_mov_b32_e32 v90, v0
	v_mov_b32_e32 v91, v0
	v_mov_b32_e32 v92, v0
	v_mov_b32_e32 v93, v0
	v_mov_b32_e32 v94, v0
	v_mov_b32_e32 v95, v0
	v_mov_b32_e32 v104, v0
	v_mov_b32_e32 v105, v0
	v_mov_b32_e32 v106, v0
	v_mov_b32_e32 v107, v0
	v_mov_b32_e32 v108, v0
	v_mov_b32_e32 v109, v0
	v_mov_b32_e32 v110, v0
	v_mov_b32_e32 v111, v0
	v_mov_b32_e32 v120, v0
	v_mov_b32_e32 v121, v0
	v_mov_b32_e32 v122, v0
	v_mov_b32_e32 v123, v0
	v_mov_b32_e32 v124, v0
	v_mov_b32_e32 v125, v0
	v_mov_b32_e32 v126, v0
	v_mov_b32_e32 v127, v0
	.p2alignl 6, 3212836864
	s_nop 0
	s_nop 0
	s_nop 0
	s_nop 0
	s_nop 0
	s_nop 0
	s_nop 0
	s_nop 0
	s_nop 0
	s_nop 0
	s_nop 0
	s_nop 0

; #define LAS __attribute__((address_space(3)))
; template <int MODE> ...
;     ...
;         if constexpr (MODE == SB) { if (it > 0) {
;             const u32x4 d0 = *(const LAS u32x4*)(lds + DONE_OFF + ((it - 1) & 1) * 32), d1 = *(const LAS u32x4*)(lds + DONE_OFF + ((it - 1) & 1) * 32 + 16);
;             if ((d0.x & d0.y & d0.z & d0.w & d1.x & d1.y & d1.z & d1.w) != 0u) break; } }
.LBB0_866:
	v_not_b32_e32 v132, v199
	v_and_b32_e32 v132, 32, v132
	v_add_u32_e32 v132, 0, v132
	v_add_u32_e32 v136, 0x21400, v132
	ds_read_b128 v[132:135], v136
	ds_read_b128 v[136:139], v136 offset:16
	s_waitcnt lgkmcnt(1)
	v_and_b32_e32 v132, v132, v133
	v_and_b32_e32 v132, v132, v134
	v_and_b32_e32 v132, v132, v135
	s_waitcnt lgkmcnt(0)
	v_and_b32_e32 v132, v132, v136
	v_and_b32_e32 v132, v132, v137
	v_and_b32_e32 v132, v132, v138
	v_and_b32_e32 v132, v132, v139
	v_cmp_eq_u32_e64 s[12:13], 0, v132
	.p2alignl 6, 3212836864

; #define LAS __attribute__((address_space(3)))
; #define ATT_LOAD(kp0_) do { _Pragma("unroll") for (int _i = 0; _i < 2; ++_i) { const int _grow = rowbase + ((kp0_) + srow + 32 * _i) * rowstride; \
;         kr[_i] = *(const u32x4*)(Kp + (size_t)_grow * ld + sch * 8); vr[_i] = *(const u32x4*)(Vp + (size_t)_grow * ld + sch * 8); } } while (0)
; template <int MODE> ...
;     ...
;     const int tid = tid_, lane = tid & 63, wid = __builtin_amdgcn_readfirstlane(tid >> 6), c15 = lane & 15, g = lane >> 4;
;     const int qw0 = q0 + 32 * wid;
;     const bool hiw = wid >= 4;
;     bf16x8 qf[2][4];
; #pragma unroll
;     for (int qt = 0; qt < 2; ++qt) { const int qrow = rowbase + (qw0 + 16 * qt + c15) * rowstride;
; #pragma unroll
;         for (int ks = 0; ks < 4; ++ks) qf[qt][ks] = *(const bf16x8*)(Qp + (size_t)qrow * ld + 32 * ks + 8 * g); }
;     f32x4 o[2][8];
; #pragma unroll
;     for (int qt = 0; qt < 2; ++qt)
; #pragma unroll
;         for (int dt = 0; dt < 8; ++dt) o[qt][dt] = (f32x4){0.f, 0.f, 0.f, 0.f};
;     float mrun[2] = {-1e30f, -1e30f}, lrun[2] = {0.f, 0.f}, Rrun[2] = {1.f, 1.f};
;     const int srow = tid >> 4, sch = tid & 15;
;     ...
;     bf16x8 pf[2][2]; bool pend = false; int bcur = 0, bprev = 0;
;     if (!pre) ATT_LOAD(ATT_KP0(0));
; #pragma unroll
;     for (int i = 0; i < 2; ++i) { *(LAS u32x4*)(lds + KOFF + (srow + 32 * i) * ROWB + sch * 16) = kr[i]; *(LAS u32x4*)(lds + VOFF + (srow + 32 * i) * ROWB + sch * 16) = vr[i]; }
;     __syncthreads();
.LBB0_909:
	s_or_b64 exec, exec, s[4:5]
	v_mov_b32_e32 v7, v168
	s_waitcnt lgkmcnt(0)
	s_barrier
	s_mov_b32 s80, 0
	v_readfirstlane_b32 s2, v7
	s_ashr_i32 s4, s2, 6
	s_lshl_b32 s38, s4, 5
	v_and_b32_e32 v24, 15, v7
	s_add_i32 s38, s38, s36
	v_bfe_u32 v25, v7, 4, 2
	v_or_b32_e32 v189, s38, v24
	v_add_u32_e32 v156, s40, v189
	v_lshlrev_b32_e32 v0, 4, v25
	v_lshl_add_u64 v[2:3], s[46:47], 0, v[0:1]
	v_or_b32_e32 v6, 16, v156
	v_mad_i64_i32 v[4:5], s[2:3], v156, s94, v[2:3]
	v_mad_i64_i32 v[2:3], s[2:3], v6, s94, v[2:3]
	global_load_dwordx4 v[112:115], v[4:5], off
	global_load_dwordx4 v[104:107], v[4:5], off offset:64
	global_load_dwordx4 v[92:95], v[4:5], off offset:128
	global_load_dwordx4 v[88:91], v[4:5], off offset:192
	global_load_dwordx4 v[116:119], v[2:3], off
	global_load_dwordx4 v[108:111], v[2:3], off offset:64
	global_load_dwordx4 v[96:99], v[2:3], off offset:128
	global_load_dwordx4 v[84:87], v[2:3], off offset:192
	v_ashrrev_i32_e32 v157, 4, v7
	s_cmp_gt_i32 s4, 3
	v_lshlrev_b32_e32 v2, 4, v24
	v_mul_lo_u32 v3, v157, s95
	s_cselect_b64 s[56:57], -1, 0
	s_cmp_lt_i32 s4, 4
	v_add3_u32 v194, 0, v2, v3
	s_cselect_b64 s[66:67], -1, 0
	s_lshl_b32 s2, s4, 7
	v_mov_b32_e32 v3, v1
	s_add_i32 s2, s2, 0
	v_lshl_add_u64 v[160:161], s[42:43], 0, v[2:3]
	v_lshl_add_u64 v[158:159], s[44:45], 0, v[2:3]
	v_lshlrev_b32_e32 v153, 2, v25
	v_bfe_u32 v2, v7, 2, 2
	s_add_i32 s2, s2, 0x21000
	v_or_b32_e32 v2, v153, v2
	v_lshlrev_b32_e32 v3, 3, v7
	v_mov_b32_e32 v4, v1
	v_mov_b32_e32 v5, v1
	v_lshl_add_u32 v195, v24, 2, s2
	v_and_b32_e32 v166, 24, v3
	v_mul_u32_u24_e32 v193, 0x120, v24
	v_mul_u32_u24_e32 v167, 0x120, v2
	v_mov_b32_e32 v2, v1
	v_mov_b32_e32 v3, v1
	v_mov_b64_e32 v[26:27], v[4:5]
	v_mov_b64_e32 v[30:31], v[4:5]
	v_mov_b64_e32 v[34:35], v[4:5]
	v_mov_b64_e32 v[38:39], v[4:5]
	v_mov_b64_e32 v[42:43], v[4:5]
	v_mov_b64_e32 v[46:47], v[4:5]
	v_mov_b64_e32 v[50:51], v[4:5]
	v_mov_b64_e32 v[54:55], v[4:5]
	v_mov_b64_e32 v[58:59], v[4:5]
	v_mov_b64_e32 v[62:63], v[4:5]
	v_mov_b64_e32 v[66:67], v[4:5]
	v_mov_b64_e32 v[70:71], v[4:5]
	v_mov_b64_e32 v[74:75], v[4:5]
	v_mov_b64_e32 v[78:79], v[4:5]
	v_mov_b64_e32 v[82:83], v[4:5]
	v_add_u32_e32 v165, s40, v157
	s_or_b32 s39, s38, 31
	v_or_b32_e32 v192, 16, v189
	v_add_u32_e32 v191, 14, v189
	v_add_u32_e32 v190, 13, v189
	v_add3_u32 v196, 0, v166, v167
	s_add_i32 s37, s36, 0xc0
	s_mov_b64 s[68:69], 0
	v_mov_b32_e32 v7, 0
	v_mov_b32_e32 v198, 0xf149f2ca
	v_mov_b64_e32 v[24:25], v[2:3]
	v_mov_b64_e32 v[28:29], v[2:3]
	v_mov_b64_e32 v[32:33], v[2:3]
	v_mov_b64_e32 v[36:37], v[2:3]
	v_mov_b64_e32 v[40:41], v[2:3]
	v_mov_b64_e32 v[44:45], v[2:3]
	v_mov_b64_e32 v[48:49], v[2:3]
	v_mov_b64_e32 v[52:53], v[2:3]
	v_mov_b64_e32 v[56:57], v[2:3]
	v_mov_b64_e32 v[60:61], v[2:3]
	v_mov_b64_e32 v[64:65], v[2:3]
	v_mov_b64_e32 v[68:69], v[2:3]
	v_mov_b64_e32 v[72:73], v[2:3]
	v_mov_b64_e32 v[76:77], v[2:3]
	v_mov_b64_e32 v[80:81], v[2:3]
	v_mov_b32_e32 v199, 0xf149f2ca
	v_mov_b32_e32 v164, 0
	s_mov_b32 s2, 0
	s_mov_b32 s3, 0
	ds_write_b128 v194, v[8:11]
	ds_write_b128 v194, v[16:19] offset:18432
	ds_write_b128 v194, v[12:15] offset:9216
	ds_write_b128 v194, v[20:23] offset:27648
	s_waitcnt lgkmcnt(0)
	s_barrier
	.p2alignl 6, 3212836864

; #define PG8_STAGE(bufoff, gbase, voff) do { _Pragma("unroll") for (int _i = 0; _i < 2; ++_i) \
;         __builtin_amdgcn_global_load_lds((const unsigned*)((const char*)(gbase) + (voff)[_i]), (LAS unsigned*)(lds + (bufoff) + ldsw + _i * 8192), 16, 0, 0); } while (0)
; #define PG8_WAIT_V(n) asm volatile("s_waitcnt vmcnt(" #n ")" ::: "memory")
; #define PG8_BAR __builtin_amdgcn_s_barrier()
; template <class EpiT>
; __device__ __forceinline__ void gemm_phase(LAS unsigned char* lds, const Gemm g, const StaticOrder& S, const EpiT& E) {
;     ...
;     f32x4 acc[2][2][4][2];
; #pragma unroll
;     for (int a = 0; a < 2; ++a)
; #pragma unroll
;         for (int b = 0; b < 2; ++b)
; #pragma unroll
;             for (int m = 0; m < 4; ++m)
; #pragma unroll
;                 for (int n = 0; n < 2; ++n) acc[a][b][m][n] = (f32x4){0.f, 0.f, 0.f, 0.f};
;     bf16x8 At[4][2], B0[2][2], B1[2][2];
;     const char* cA = (const char*)g.A + (size_t)cur.pm * tstepA + (size_t)cur.pn * g.a_koff * 2; const char* cB = (const char*)g.Bt + (size_t)cur.pn * tstepB;
;     PG8_STAGE(PG8_SB(0, 0), cB, voffB); PG8_STAGE(PG8_SB(0, 1), cB + hstepB, voffB); PG8_STAGE(PG8_SA(0, 0), cA, voffA); PG8_STAGE(PG8_SA(0, 1), cA + hstepA, voffA);
;     if (wr == 1) PG8_BAR;
;     PG8_WAIT_V(2); PG8_BAR;
;     PG8_STAGE(PG8_SB(1, 0), cB + kstep, voffB); PG8_STAGE(PG8_SA(1, 0), cA + kstep, voffA); PG8_STAGE(PG8_SB(1, 1), cB + hstepB + kstep, voffB);
;     PG8_WAIT_V(6); PG8_BAR;
;     for (;;) {
;         const bool has_next = S.next(ui + 1, nxt);
;         const char* nA = has_next ? (const char*)g.A + (size_t)nxt.pm * tstepA + (size_t)nxt.pn * g.a_koff * 2 : cA; const char* nB = has_next ? (const char*)g.Bt + (size_t)nxt.pn * tstepB : cB;
;         for (int t = 0; t < nt; t += 2) {
.LBB0_1031:
	s_add_u32 s18, s18, 0x84080
	s_addc_u32 s19, s19, 0
	s_add_u32 s53, s20, 0x100
	v_mov_b32_e32 v0, 0
	s_addc_u32 s54, s21, 0
	s_mov_b32 s55, -2
	v_mov_b32_e32 v1, v0
	v_mov_b32_e32 v2, v0
	v_mov_b32_e32 v3, v0
	v_mov_b32_e32 v4, v0
	v_mov_b32_e32 v5, v0
	v_mov_b32_e32 v6, v0
	v_mov_b32_e32 v7, v0
	v_mov_b32_e32 v16, v0
	v_mov_b32_e32 v17, v0
	v_mov_b32_e32 v18, v0
	v_mov_b32_e32 v19, v0
	v_mov_b32_e32 v20, v0
	v_mov_b32_e32 v21, v0
	v_mov_b32_e32 v22, v0
	v_mov_b32_e32 v23, v0
	v_mov_b32_e32 v32, v0
	v_mov_b32_e32 v33, v0
	v_mov_b32_e32 v34, v0
	v_mov_b32_e32 v35, v0
	v_mov_b32_e32 v36, v0
	v_mov_b32_e32 v37, v0
	v_mov_b32_e32 v38, v0
	v_mov_b32_e32 v39, v0
	v_mov_b32_e32 v48, v0
	v_mov_b32_e32 v49, v0
	v_mov_b32_e32 v50, v0
	v_mov_b32_e32 v51, v0
	v_mov_b32_e32 v52, v0
	v_mov_b32_e32 v53, v0
	v_mov_b32_e32 v54, v0
	v_mov_b32_e32 v55, v0
	v_mov_b32_e32 v8, v0
	v_mov_b32_e32 v9, v0
	v_mov_b32_e32 v10, v0
	v_mov_b32_e32 v11, v0
	v_mov_b32_e32 v12, v0
	v_mov_b32_e32 v13, v0
	v_mov_b32_e32 v14, v0
	v_mov_b32_e32 v15, v0
	v_mov_b32_e32 v24, v0
	v_mov_b32_e32 v25, v0
	v_mov_b32_e32 v26, v0
	v_mov_b32_e32 v27, v0
	v_mov_b32_e32 v28, v0
	v_mov_b32_e32 v29, v0
	v_mov_b32_e32 v30, v0
	v_mov_b32_e32 v31, v0
	v_mov_b32_e32 v40, v0
	v_mov_b32_e32 v41, v0
	v_mov_b32_e32 v42, v0
	v_mov_b32_e32 v43, v0
	v_mov_b32_e32 v44, v0
	v_mov_b32_e32 v45, v0
	v_mov_b32_e32 v46, v0
	v_mov_b32_e32 v47, v0
	v_mov_b32_e32 v56, v0
	v_mov_b32_e32 v57, v0
	v_mov_b32_e32 v58, v0
	v_mov_b32_e32 v59, v0
	v_mov_b32_e32 v60, v0
	v_mov_b32_e32 v61, v0
	v_mov_b32_e32 v62, v0
	v_mov_b32_e32 v63, v0
	v_mov_b32_e32 v64, v0
	v_mov_b32_e32 v65, v0
	v_mov_b32_e32 v66, v0
	v_mov_b32_e32 v67, v0
	v_mov_b32_e32 v68, v0
	v_mov_b32_e32 v69, v0
	v_mov_b32_e32 v70, v0
	v_mov_b32_e32 v71, v0
	v_mov_b32_e32 v80, v0
	v_mov_b32_e32 v81, v0
	v_mov_b32_e32 v82, v0
	v_mov_b32_e32 v83, v0
	v_mov_b32_e32 v84, v0
	v_mov_b32_e32 v85, v0
	v_mov_b32_e32 v86, v0
	v_mov_b32_e32 v87, v0
	v_mov_b32_e32 v96, v0
	v_mov_b32_e32 v97, v0
	v_mov_b32_e32 v98, v0
	v_mov_b32_e32 v99, v0
	v_mov_b32_e32 v100, v0
	v_mov_b32_e32 v101, v0
	v_mov_b32_e32 v102, v0
	v_mov_b32_e32 v103, v0
	v_mov_b32_e32 v112, v0
	v_mov_b32_e32 v113, v0
	v_mov_b32_e32 v114, v0
	v_mov_b32_e32 v115, v0
	v_mov_b32_e32 v116, v0
	v_mov_b32_e32 v117, v0
	v_mov_b32_e32 v118, v0
	v_mov_b32_e32 v119, v0
	v_mov_b32_e32 v72, v0
	v_mov_b32_e32 v73, v0
	v_mov_b32_e32 v74, v0
	v_mov_b32_e32 v75, v0
	v_mov_b32_e32 v76, v0
	v_mov_b32_e32 v77, v0
	v_mov_b32_e32 v78, v0
	v_mov_b32_e32 v79, v0
	v_mov_b32_e32 v88, v0
	v_mov_b32_e32 v89, v0
	v_mov_b32_e32 v90, v0
	v_mov_b32_e32 v91, v0
	v_mov_b32_e32 v92, v0
	v_mov_b32_e32 v93, v0
	v_mov_b32_e32 v94, v0
	v_mov_b32_e32 v95, v0
	v_mov_b32_e32 v104, v0
	v_mov_b32_e32 v105, v0
	v_mov_b32_e32 v106, v0
	v_mov_b32_e32 v107, v0
	v_mov_b32_e32 v108, v0
	v_mov_b32_e32 v109, v0
	v_mov_b32_e32 v110, v0
	v_mov_b32_e32 v111, v0
	v_mov_b32_e32 v120, v0
	v_mov_b32_e32 v121, v0
	v_mov_b32_e32 v122, v0
	v_mov_b32_e32 v123, v0
	v_mov_b32_e32 v124, v0
	v_mov_b32_e32 v125, v0
	v_mov_b32_e32 v126, v0
	v_mov_b32_e32 v127, v0
	.p2alignl 6, 3212836864
	s_nop 0
	s_nop 0
	s_nop 0
	s_nop 0
	s_nop 0
	s_nop 0
	s_nop 0
	s_nop 0
	s_nop 0
	s_nop 0
	s_nop 0
	s_nop 0
